# single job queue with diff-job reorder (no sub-queue stealing tail) + dequeue atomics issued before the preceding barrier
# speedup vs baseline: 1.0008x; 1.0008x over previous
; DI int next_job(u32* ctr, unsigned char* smem) {
;   int* sj = (int*)(smem + SJOB_OFF);
;   __syncthreads();
;   if (threadIdx.x == 0) *sj = (int)atomicAdd(ctr, 1u);
;   __syncthreads();
;   return *sj;
; }
.LBB0_360:
	s_mov_b64 s[2:3], exec
	v_readlane_b32 s4, v253, 1
	v_readlane_b32 s5, v253, 2
	s_and_b64 s[4:5], s[2:3], s[4:5]
	s_mov_b64 exec, s[4:5]
	s_cbranch_execz .Lpq_360
	v_mov_b32_e32 v2, 1
	s_nop 3
	global_atomic_add v2, v1, v2, s[52:53] sc0
